# attention K/V stage DMAs with scalar running bases + constant 32-bit lane offset (no 64-bit VALU address arithmetic in the tile loop), on top of v165
# speedup vs baseline: 1.0107x; 1.0107x over previous
.LBB0_1116:
	s_mov_b64 s[54:55], s[52:53]
	s_mov_b64 s[56:57], s[48:49]
	v_mov_b32_e32 v2, v0
	v_mov_b32_e32 v3, v0
	v_mov_b32_e32 v1, v0
	v_mov_b64_e32 v[22:23], v[2:3]
	v_mov_b64_e32 v[26:27], v[2:3]
	v_mov_b64_e32 v[30:31], v[2:3]
	v_mov_b64_e32 v[34:35], v[2:3]
	v_mov_b64_e32 v[38:39], v[2:3]
	v_mov_b64_e32 v[42:43], v[2:3]
	v_mov_b64_e32 v[46:47], v[2:3]
	v_mov_b64_e32 v[50:51], v[2:3]
	v_mov_b64_e32 v[54:55], v[2:3]
	v_mov_b64_e32 v[58:59], v[2:3]
	v_mov_b64_e32 v[62:63], v[2:3]
	v_mov_b64_e32 v[66:67], v[2:3]
	v_mov_b64_e32 v[70:71], v[2:3]
	v_mov_b64_e32 v[74:75], v[2:3]
	v_mov_b64_e32 v[78:79], v[2:3]
	v_mov_b64_e32 v[82:83], v[2:3]
	s_mov_b32 s91, s93
	s_mov_b32 s90, s92
	s_sub_i32 s50, 63, s87
	v_mov_b32_e32 v143, 0xf149f2ca
	v_mov_b64_e32 v[146:147], v[140:141]
	v_mov_b64_e32 v[148:149], v[138:139]
	v_mov_b64_e32 v[20:21], v[0:1]
	v_mov_b64_e32 v[24:25], v[0:1]
	v_mov_b64_e32 v[28:29], v[0:1]
	v_mov_b64_e32 v[32:33], v[0:1]
	v_mov_b64_e32 v[36:37], v[0:1]
	v_mov_b64_e32 v[40:41], v[0:1]
	v_mov_b64_e32 v[44:45], v[0:1]
	v_mov_b64_e32 v[48:49], v[0:1]
	v_mov_b64_e32 v[52:53], v[0:1]
	v_mov_b64_e32 v[56:57], v[0:1]
	v_mov_b64_e32 v[60:61], v[0:1]
	v_mov_b64_e32 v[64:65], v[0:1]
	v_mov_b64_e32 v[68:69], v[0:1]
	v_mov_b64_e32 v[72:73], v[0:1]
	v_mov_b64_e32 v[76:77], v[0:1]
	v_mov_b64_e32 v[80:81], v[0:1]
	v_mov_b32_e32 v1, 0
	s_mov_b32 s70, 0
	s_waitcnt vmcnt(0)
.LBB0_1117:
	s_waitcnt vmcnt(0)
	s_waitcnt lgkmcnt(0)
	s_barrier
	s_and_b32 s92, s70, 1
	s_add_i32 s70, s70, 1
	s_lshl_b32 s71, s92, 15
	v_add_u32_e32 v2, s71, v160
	v_add_u32_e32 v3, v2, v153
	v_add_u32_e32 v124, v2, v154
	v_add_u32_e32 v125, v2, v155
	v_add_u32_e32 v2, v2, v156
	ds_read_b128 v[84:87], v3
	ds_read_b128 v[88:91], v3 offset:2048
	ds_read_b128 v[92:95], v124
	ds_read_b128 v[96:99], v124 offset:2048
	ds_read_b128 v[100:103], v125
	ds_read_b128 v[104:107], v125 offset:2048
	ds_read_b128 v[108:111], v2
	ds_read_b128 v[112:115], v2 offset:2048
	ds_read_b128 v[116:119], v3 offset:16384
	ds_read_b128 v[166:169], v3 offset:18432
	ds_read_b128 v[120:123], v124 offset:16384
	ds_read_b128 v[170:173], v124 offset:18432
	ds_read_b128 v[174:177], v125 offset:16384
	ds_read_b128 v[178:181], v125 offset:18432
	ds_read_b128 v[182:185], v2 offset:16384
	ds_read_b128 v[186:189], v2 offset:18432
	s_cmp_lt_i32 s70, s69
	s_cbranch_scc0 .Latt_k_done
	s_xor_b32 s0, s71, 0x8000
	s_add_i32 s1, s79, s0
	s_add_u32 s54, s54, 0x40000
	s_addc_u32 s55, s55, 0
	s_mov_b32 m0, s1
	s_add_u32 s58, s54, 0x4000
	global_load_lds_dwordx4 v140, s[54:55]
	s_addc_u32 s59, s55, 0
	s_add_i32 m0, s1, 0x800
	s_nop 0
	global_load_lds_dwordx4 v140, s[58:59]
	s_add_u32 s58, s54, 0x20000
	s_addc_u32 s59, s55, 0
	s_add_i32 m0, s1, 0x4000
	s_nop 0
	global_load_lds_dwordx4 v140, s[58:59]
	s_add_u32 s58, s54, 0x24000
	s_addc_u32 s59, s55, 0
	s_add_i32 m0, s1, 0x4800
	s_nop 0
	global_load_lds_dwordx4 v140, s[58:59]
.Latt_k_done:
	s_waitcnt lgkmcnt(14)
	v_mfma_f32_16x16x32_bf16 v[128:131], v[84:87], v[4:7], 0
	v_mfma_f32_16x16x32_bf16 v[124:127], v[88:91], v[4:7], 0
	s_waitcnt lgkmcnt(12)
	v_mfma_f32_16x16x32_bf16 v[128:131], v[92:95], v[8:11], v[128:131]
	v_mfma_f32_16x16x32_bf16 v[124:127], v[96:99], v[8:11], v[124:127]
	s_waitcnt lgkmcnt(10)
	v_mfma_f32_16x16x32_bf16 v[128:131], v[100:103], v[12:15], v[128:131]
	v_mfma_f32_16x16x32_bf16 v[124:127], v[104:107], v[12:15], v[124:127]
	s_waitcnt lgkmcnt(8)
	v_mfma_f32_16x16x32_bf16 v[128:131], v[108:111], v[16:19], v[128:131]
	v_mfma_f32_16x16x32_bf16 v[124:127], v[112:115], v[16:19], v[124:127]
	s_waitcnt lgkmcnt(6)
	v_mfma_f32_16x16x32_bf16 v[84:87], v[116:119], v[4:7], 0
	v_mfma_f32_16x16x32_bf16 v[92:95], v[166:169], v[4:7], 0
	s_waitcnt lgkmcnt(4)
	v_mfma_f32_16x16x32_bf16 v[84:87], v[120:123], v[8:11], v[84:87]
	v_mfma_f32_16x16x32_bf16 v[92:95], v[170:173], v[8:11], v[92:95]
	s_waitcnt lgkmcnt(2)
	v_mfma_f32_16x16x32_bf16 v[84:87], v[174:177], v[12:15], v[84:87]
	v_mfma_f32_16x16x32_bf16 v[92:95], v[178:181], v[12:15], v[92:95]
	s_waitcnt lgkmcnt(0)
	v_mfma_f32_16x16x32_bf16 v[120:123], v[182:185], v[16:19], v[84:87]
	v_mfma_f32_16x16x32_bf16 v[116:119], v[186:189], v[16:19], v[92:95]
	v_add_u32_e32 v2, s71, v157
	v_add_u32_e32 v3, v2, v158
	v_add_u32_e32 v145, v2, v159
	ds_read_b128 v[100:103], v3
	ds_read_b128 v[88:91], v3 offset:2048
	ds_read_b128 v[112:115], v145
	ds_read_b128 v[104:107], v145 offset:2048
	ds_read_b128 v[92:95], v3 offset:4096
	ds_read_b128 v[84:87], v3 offset:6144
	ds_read_b128 v[108:111], v145 offset:4096
	ds_read_b128 v[96:99], v145 offset:6144
	ds_read_b128 v[194:197], v3 offset:8192
	ds_read_b128 v[198:201], v3 offset:10240
	ds_read_b128 v[202:205], v145 offset:8192
	ds_read_b128 v[206:209], v145 offset:10240
	ds_read_b128 v[210:213], v3 offset:12288
	ds_read_b128 v[214:217], v3 offset:14336
	ds_read_b128 v[218:221], v145 offset:12288
	ds_read_b128 v[222:225], v145 offset:14336
	s_cmp_lt_i32 s70, s69
	s_cbranch_scc0 .Latt_v_done
	s_xor_b32 s0, s71, 0x8000
	s_add_i32 s0, s80, s0
	s_add_u32 s56, s56, 0x80
	s_addc_u32 s57, s57, 0
	s_mov_b32 m0, s0
	s_add_u32 s58, s56, 0x100000
	global_load_lds_dwordx4 v138, s[56:57]
	s_addc_u32 s59, s57, 0
	s_add_i32 m0, s0, 0x2000
	s_nop 0
	global_load_lds_dwordx4 v138, s[58:59]
	s_add_u32 s58, s56, 0x200000
	s_addc_u32 s59, s57, 0
	s_add_i32 m0, s0, 0x4000
	s_nop 0
	global_load_lds_dwordx4 v138, s[58:59]
	s_add_u32 s58, s56, 0x300000
	s_addc_u32 s59, s57, 0
	s_add_i32 m0, s0, 0x6000
	s_nop 0
	global_load_lds_dwordx4 v138, s[58:59]

.LBB0_1126:
	v_sub_f32_e32 v128, v128, v143
	v_exp_f32_e32 v128, v128
	v_sub_f32_e32 v129, v129, v143
	v_exp_f32_e32 v129, v129
	v_sub_f32_e32 v130, v130, v143
	v_exp_f32_e32 v130, v130
	v_sub_f32_e32 v131, v131, v143
	v_exp_f32_e32 v131, v131
	v_sub_f32_e32 v124, v124, v143
	v_add_f32_e32 v165, 0, v128
	v_exp_f32_e32 v124, v124
	v_sub_f32_e32 v125, v125, v143
	v_add_f32_e32 v165, v129, v165
	v_exp_f32_e32 v125, v125
	v_sub_f32_e32 v126, v126, v143
	v_add_f32_e32 v165, v130, v165
	v_exp_f32_e32 v126, v126
	v_sub_f32_e32 v127, v127, v143
	v_add_f32_e32 v165, v131, v165
	v_exp_f32_e32 v127, v127
	v_sub_f32_e32 v120, v120, v143
	v_add_f32_e32 v165, v124, v165
	v_exp_f32_e32 v166, v120
	v_sub_f32_e32 v120, v121, v143
	v_add_f32_e32 v165, v125, v165
	v_exp_f32_e32 v167, v120
	v_sub_f32_e32 v120, v122, v143
	v_add_f32_e32 v165, v126, v165
	v_exp_f32_e32 v168, v120
	v_sub_f32_e32 v120, v123, v143
	v_add_f32_e32 v165, v127, v165
	v_exp_f32_e32 v123, v120
	v_sub_f32_e32 v116, v116, v143
	v_add_f32_e32 v120, v166, v165
	v_exp_f32_e32 v165, v116
	v_sub_f32_e32 v116, v117, v143
	v_add_f32_e32 v120, v167, v120
	v_exp_f32_e32 v117, v116
	v_sub_f32_e32 v116, v118, v143
	v_add_f32_e32 v120, v168, v120
	v_exp_f32_e32 v169, v116
	v_sub_f32_e32 v116, v119, v143
	v_add_f32_e32 v120, v123, v120
	v_exp_f32_e32 v170, v116
	v_add_f32_e32 v116, v165, v120
	v_add_f32_e32 v116, v117, v116
	v_add_f32_e32 v116, v169, v116
	v_add_f32_e32 v116, v170, v116
	v_fmac_f32_e32 v116, v1, v2
	v_cvt_pk_bf16_f32 v118, v128, v129
	v_cvt_pk_bf16_f32 v119, v130, v131
	v_cvt_pk_bf16_f32 v120, v124, v125
	v_cvt_pk_bf16_f32 v121, v126, v127
	v_cvt_pk_bf16_f32 v122, v166, v167
	v_cvt_pk_bf16_f32 v123, v168, v123
	v_cvt_pk_bf16_f32 v124, v165, v117
	v_cvt_pk_bf16_f32 v125, v169, v170
	s_waitcnt lgkmcnt(0)
	v_mfma_f32_16x16x32_bf16 v[80:83], v[100:103], v[118:121], v[80:83]
	v_mfma_f32_16x16x32_bf16 v[76:79], v[88:91], v[118:121], v[76:79]
	v_mfma_f32_16x16x32_bf16 v[72:75], v[92:95], v[118:121], v[72:75]
	v_mfma_f32_16x16x32_bf16 v[68:71], v[84:87], v[118:121], v[68:71]
	v_mfma_f32_16x16x32_bf16 v[80:83], v[112:115], v[122:125], v[80:83]
	v_mfma_f32_16x16x32_bf16 v[76:79], v[104:107], v[122:125], v[76:79]
	v_mfma_f32_16x16x32_bf16 v[72:75], v[108:111], v[122:125], v[72:75]
	v_mfma_f32_16x16x32_bf16 v[68:71], v[96:99], v[122:125], v[68:71]
	ds_read_b128 v[84:87], v3 offset:16384
	ds_read_b128 v[88:91], v3 offset:18432
	ds_read_b128 v[92:95], v145 offset:16384
	ds_read_b128 v[96:99], v145 offset:18432
	ds_read_b128 v[100:103], v3 offset:20480
	ds_read_b128 v[104:107], v3 offset:22528
	ds_read_b128 v[108:111], v145 offset:20480
	ds_read_b128 v[112:115], v145 offset:22528
	ds_read_b128 v[126:129], v3 offset:24576
	ds_read_b128 v[166:169], v3 offset:26624
	ds_read_b128 v[170:173], v145 offset:24576
	ds_read_b128 v[174:177], v145 offset:26624
	ds_read_b128 v[178:181], v3 offset:28672
	ds_read_b128 v[182:185], v3 offset:30720
	ds_read_b128 v[186:189], v145 offset:28672
	ds_read_b128 v[190:193], v145 offset:30720
	v_mfma_f32_16x16x32_bf16 v[64:67], v[194:197], v[118:121], v[64:67]
	v_mfma_f32_16x16x32_bf16 v[60:63], v[198:201], v[118:121], v[60:63]
	v_mfma_f32_16x16x32_bf16 v[56:59], v[210:213], v[118:121], v[56:59]
	v_mfma_f32_16x16x32_bf16 v[52:55], v[214:217], v[118:121], v[52:55]
	v_mfma_f32_16x16x32_bf16 v[64:67], v[202:205], v[122:125], v[64:67]
	v_mfma_f32_16x16x32_bf16 v[60:63], v[206:209], v[122:125], v[60:63]
	v_mfma_f32_16x16x32_bf16 v[56:59], v[218:221], v[122:125], v[56:59]
	v_mfma_f32_16x16x32_bf16 v[52:55], v[222:225], v[122:125], v[52:55]
	s_waitcnt lgkmcnt(8)
	v_mfma_f32_16x16x32_bf16 v[48:51], v[84:87], v[118:121], v[48:51]
	v_mfma_f32_16x16x32_bf16 v[44:47], v[88:91], v[118:121], v[44:47]
	v_mfma_f32_16x16x32_bf16 v[40:43], v[100:103], v[118:121], v[40:43]
	v_mfma_f32_16x16x32_bf16 v[36:39], v[104:107], v[118:121], v[36:39]
	v_mfma_f32_16x16x32_bf16 v[48:51], v[92:95], v[122:125], v[48:51]
	v_mfma_f32_16x16x32_bf16 v[44:47], v[96:99], v[122:125], v[44:47]
	v_mfma_f32_16x16x32_bf16 v[40:43], v[108:111], v[122:125], v[40:43]
	v_mfma_f32_16x16x32_bf16 v[36:39], v[112:115], v[122:125], v[36:39]
	s_waitcnt lgkmcnt(0)
	v_mfma_f32_16x16x32_bf16 v[32:35], v[126:129], v[118:121], v[32:35]
	v_mfma_f32_16x16x32_bf16 v[28:31], v[166:169], v[118:121], v[28:31]
	v_mfma_f32_16x16x32_bf16 v[24:27], v[178:181], v[118:121], v[24:27]
	v_mfma_f32_16x16x32_bf16 v[20:23], v[182:185], v[118:121], v[20:23]
	v_mfma_f32_16x16x32_bf16 v[32:35], v[170:173], v[122:125], v[32:35]
	v_mfma_f32_16x16x32_bf16 v[28:31], v[174:177], v[122:125], v[28:31]
	v_mfma_f32_16x16x32_bf16 v[24:27], v[186:189], v[122:125], v[24:27]
	v_mfma_f32_16x16x32_bf16 v[20:23], v[190:193], v[122:125], v[20:23]
	s_add_i32 s50, s50, 64
	s_cmp_eq_u32 s69, s70
	s_cbranch_scc1 .LBB0_1129
	v_mov_b32_e32 v1, v116
	s_branch .LBB0_1117
